# same loop, padded so code after it keeps baseline addresses
# speedup vs baseline: 1.0132x; 1.0011x over previous
; #define LAS __attribute__((address_space(3)))
; __device__ __forceinline__ float bflo(unsigned w) { return __uint_as_float(w << 16); }
; __device__ __forceinline__ float bfhi(unsigned w) { return __uint_as_float(w & 0xffff0000u); }
; __device__ __forceinline__ unsigned pk2(float lo, float hi) { return pg8::cvt_pk_bf16(lo, hi); }
; __device__ __forceinline__ void mlstm_seq(LAS unsigned char* lds, int tid_in, int b, int h, const bf16_t* z1, const bf16_t* z2a, const float* g_hnorm, bf16_t* yb, const unsigned char* ws) {
;     ...
;             for (int g = 0; g < 4; ++g) zo[tb][g] = pzo[tb][g];
;         const float wi0 = pwi0, wi1 = pwi1, wq = pwq, eq = peq, dq0 = pdq, dn = pdn;
;     ...
; #pragma unroll
;         for (int tb = 0; tb < 2; ++tb) {
;             const int t = 32 * tb + r;
;             const float inv = INV[t];
;             const f32x4 pa = *(const LAS f32x4*)(PR + t * 8), pb = *(const LAS f32x4*)(PR + t * 8 + 4);
;             const float rn = inv * rsqrtf(inv * inv * ((pa[0] + pa[1]) + (pa[2] + pa[3]) + (pb[0] + pb[1]) + (pb[2] + pb[3])) * (1.f / 256.f) + EPSN);
; #pragma unroll
;             for (int g = 0; g < 4; ++g) {
;                 const int dv = 32 * wid + 8 * g + 4 * hh;
;                 u32x2 w; w.x = pk2(Z[tb][4 * g] * rn * bflo(zo[tb][g].x), Z[tb][4 * g + 1] * rn * bfhi(zo[tb][g].x));
;                 w.y = pk2(Z[tb][4 * g + 2] * rn * bflo(zo[tb][g].y), Z[tb][4 * g + 3] * rn * bfhi(zo[tb][g].y));
;                 *(u32x2*)(yb + (tok0 + t) * Z2_LD + h * 256 + dv) = w;
;             }
;         }
.Lml_nostage:
	s_mov_b64 s[12:13], 0x80000
	v_mul_f32_e32 v140, v226, v226
	v_add_f32_e32 v141, v223, v222
	v_add_f32_e32 v142, v224, v225
	v_add_f32_e32 v143, v232, v233
	v_add_f32_e32 v146, v230, v231
	v_add_f32_e32 v141, v141, v142
	v_add_f32_e32 v141, v141, v146
	v_add_f32_e32 v141, v143, v141
	v_mul_f32_e32 v141, v140, v141
	v_fmamk_f32 v141, v141, 0x3b800000, v221
	v_mul_f32_e32 v142, 0x4b800000, v141
	v_cmp_gt_f32_e32 vcc, s77, v141
	s_nop 1
	v_cndmask_b32_e32 v141, v141, v142, vcc
	v_rsq_f32_e32 v141, v141
	s_nop 0
	v_mul_f32_e32 v142, 0x45800000, v141
	v_cndmask_b32_e32 v141, v141, v142, vcc
	v_mul_f32_e32 v145, v226, v141
	v_mul_f32_e32 v82, v82, v145
	v_lshlrev_b32_e32 v140, 16, v180
	v_mul_f32_e32 v83, v83, v145
	v_and_b32_e32 v141, 0xffff0000, v180
	v_mul_f32_e32 v82, v82, v140
	v_mul_f32_e32 v83, v83, v141
	v_mul_f32_e32 v84, v84, v145
	v_lshlrev_b32_e32 v142, 16, v181
	v_mul_f32_e32 v85, v85, v145
	v_and_b32_e32 v143, 0xffff0000, v181
	v_cvt_pk_bf16_f32 v82, v82, v83
	v_mul_f32_e32 v84, v84, v142
	v_mul_f32_e32 v85, v85, v143
	v_cvt_pk_bf16_f32 v83, v84, v85
	global_store_dwordx2 v[136:137], v[82:83], off
	v_mul_f32_e32 v86, v86, v145
	v_lshlrev_b32_e32 v140, 16, v178
	v_mul_f32_e32 v87, v87, v145
	v_and_b32_e32 v141, 0xffff0000, v178
	v_mul_f32_e32 v86, v86, v140
	v_mul_f32_e32 v87, v87, v141
	v_mul_f32_e32 v88, v88, v145
	v_lshlrev_b32_e32 v142, 16, v179
	v_mul_f32_e32 v89, v89, v145
	v_and_b32_e32 v143, 0xffff0000, v179
	v_cvt_pk_bf16_f32 v86, v86, v87
	v_mul_f32_e32 v88, v88, v142
	v_mul_f32_e32 v89, v89, v143
	v_cvt_pk_bf16_f32 v87, v88, v89
	global_store_dwordx2 v[136:137], v[86:87], off offset:16
	v_mul_f32_e32 v90, v90, v145
	v_lshlrev_b32_e32 v140, 16, v174
	v_mul_f32_e32 v91, v91, v145
	v_and_b32_e32 v141, 0xffff0000, v174
	v_mul_f32_e32 v90, v90, v140
	v_mul_f32_e32 v91, v91, v141
	v_mul_f32_e32 v92, v92, v145
	v_lshlrev_b32_e32 v142, 16, v175
	v_mul_f32_e32 v93, v93, v145
	v_and_b32_e32 v143, 0xffff0000, v175
	v_cvt_pk_bf16_f32 v90, v90, v91
	v_mul_f32_e32 v92, v92, v142
	v_mul_f32_e32 v93, v93, v143
	v_cvt_pk_bf16_f32 v91, v92, v93
	global_store_dwordx2 v[136:137], v[90:91], off offset:32
	v_mul_f32_e32 v94, v94, v145
	v_lshlrev_b32_e32 v140, 16, v166
	v_mul_f32_e32 v95, v95, v145
	v_and_b32_e32 v141, 0xffff0000, v166
	v_mul_f32_e32 v94, v94, v140
	v_mul_f32_e32 v95, v95, v141
	v_mul_f32_e32 v96, v96, v145
	v_lshlrev_b32_e32 v142, 16, v167
	v_mul_f32_e32 v97, v97, v145
	v_and_b32_e32 v143, 0xffff0000, v167
	v_cvt_pk_bf16_f32 v94, v94, v95
	v_mul_f32_e32 v96, v96, v142
	v_mul_f32_e32 v97, v97, v143
	v_cvt_pk_bf16_f32 v95, v96, v97
	global_store_dwordx2 v[136:137], v[94:95], off offset:48
	v_lshl_add_u64 v[150:151], v[150:151], 0, s[12:13]
	v_lshl_add_u64 v[172:173], v[172:173], 0, s[12:13]
	v_lshl_add_u64 v[168:169], v[168:169], 0, s[12:13]
	s_mov_b64 s[12:13], 0x68000
	v_mul_f32_e32 v140, v227, v227
	v_add_f32_e32 v141, v235, v234
	v_add_f32_e32 v142, v236, v237
	v_add_f32_e32 v143, v248, v249
	v_add_f32_e32 v146, v246, v247
	v_add_f32_e32 v141, v141, v142
	v_add_f32_e32 v141, v141, v146
	v_add_f32_e32 v141, v143, v141
	v_mul_f32_e32 v141, v140, v141
	v_fmamk_f32 v141, v141, 0x3b800000, v221
	v_mul_f32_e32 v142, 0x4b800000, v141
	v_cmp_gt_f32_e32 vcc, s77, v141
	s_nop 1
	v_cndmask_b32_e32 v141, v141, v142, vcc
	v_rsq_f32_e32 v141, v141
	s_nop 0
	v_mul_f32_e32 v142, 0x45800000, v141
	v_cndmask_b32_e32 v141, v141, v142, vcc
	v_mul_f32_e32 v145, v227, v141
	v_mul_f32_e32 v66, v66, v145
	v_lshlrev_b32_e32 v140, 16, v158
	v_mul_f32_e32 v67, v67, v145
	v_and_b32_e32 v141, 0xffff0000, v158
	v_mul_f32_e32 v66, v66, v140
	v_mul_f32_e32 v67, v67, v141
	v_mul_f32_e32 v68, v68, v145
	v_lshlrev_b32_e32 v142, 16, v159
	v_mul_f32_e32 v69, v69, v145
	v_and_b32_e32 v143, 0xffff0000, v159
	v_cvt_pk_bf16_f32 v66, v66, v67
	v_mul_f32_e32 v68, v68, v142
	v_mul_f32_e32 v69, v69, v143
	v_cvt_pk_bf16_f32 v67, v68, v69
	global_store_dwordx2 v[138:139], v[66:67], off
	v_mul_f32_e32 v70, v70, v145
	v_lshlrev_b32_e32 v140, 16, v156
	v_mul_f32_e32 v71, v71, v145
	v_and_b32_e32 v141, 0xffff0000, v156
	v_mul_f32_e32 v70, v70, v140
	v_mul_f32_e32 v71, v71, v141
	v_mul_f32_e32 v72, v72, v145
	v_lshlrev_b32_e32 v142, 16, v157
	v_mul_f32_e32 v73, v73, v145
	v_and_b32_e32 v143, 0xffff0000, v157
	v_cvt_pk_bf16_f32 v70, v70, v71
	v_mul_f32_e32 v72, v72, v142
	v_mul_f32_e32 v73, v73, v143
	v_cvt_pk_bf16_f32 v71, v72, v73
	global_store_dwordx2 v[138:139], v[70:71], off offset:16
	v_mul_f32_e32 v74, v74, v145
	v_lshlrev_b32_e32 v140, 16, v154
	v_mul_f32_e32 v75, v75, v145
	v_and_b32_e32 v141, 0xffff0000, v154
	v_mul_f32_e32 v74, v74, v140
	v_mul_f32_e32 v75, v75, v141
	v_mul_f32_e32 v76, v76, v145
	v_lshlrev_b32_e32 v142, 16, v155
	v_mul_f32_e32 v77, v77, v145
	v_and_b32_e32 v143, 0xffff0000, v155
	v_cvt_pk_bf16_f32 v74, v74, v75
	v_mul_f32_e32 v76, v76, v142
	v_mul_f32_e32 v77, v77, v143
	v_cvt_pk_bf16_f32 v75, v76, v77
	global_store_dwordx2 v[138:139], v[74:75], off offset:32
	v_mul_f32_e32 v78, v78, v145
	v_lshlrev_b32_e32 v140, 16, v152
	v_mul_f32_e32 v79, v79, v145
	v_and_b32_e32 v141, 0xffff0000, v152
	v_mul_f32_e32 v78, v78, v140
	v_mul_f32_e32 v79, v79, v141
	v_mul_f32_e32 v80, v80, v145
	v_lshlrev_b32_e32 v142, 16, v153
	v_mul_f32_e32 v81, v81, v145
	v_and_b32_e32 v143, 0xffff0000, v153
	v_cvt_pk_bf16_f32 v78, v78, v79
	v_mul_f32_e32 v80, v80, v142
	v_mul_f32_e32 v81, v81, v143
	v_cvt_pk_bf16_f32 v79, v80, v81
	global_store_dwordx2 v[138:139], v[78:79], off offset:48
	v_lshl_add_u64 v[160:161], v[160:161], 0, s[92:93]
	v_lshl_add_u64 v[162:163], v[162:163], 0, s[94:95]
	v_lshl_add_u64 v[170:171], v[170:171], 0, s[16:17]
	v_lshl_add_u64 v[176:177], v[176:177], 0, s[12:13]
	s_add_i32 s14, s14, -1
	s_waitcnt vmcnt(8)
	v_mov_b64_e32 v[180:181], v[182:183]
	v_mov_b64_e32 v[178:179], v[184:185]
	v_mov_b64_e32 v[174:175], v[186:187]
	v_mov_b64_e32 v[166:167], v[188:189]
	v_mov_b64_e32 v[158:159], v[190:191]
	v_mov_b64_e32 v[156:157], v[192:193]
	v_mov_b64_e32 v[154:155], v[194:195]
	v_mov_b64_e32 v[152:153], v[196:197]
	v_mov_b32_e32 v250, v217
	v_mov_b32_e32 v251, v218
	v_mov_b32_e32 v216, v219
	v_mov_b32_e32 v164, v215
	s_cmp_eq_u32 s14, 0
	s_cbranch_scc1 .LBB0_93
	s_waitcnt lgkmcnt(0)
	s_barrier
	s_branch .Lml_loop
	s_nop 0
	s_nop 0
	s_nop 0
	s_nop 0
	s_nop 0
	s_nop 0
	s_nop 0
	s_nop 0
	s_nop 0
	s_nop 0
	s_nop 0
	s_nop 0
	s_nop 0
	s_nop 0
	s_nop 0
	s_nop 0
	s_nop 0
	s_nop 0
	s_nop 0
	s_nop 0
	s_nop 0
	s_nop 0
	s_nop 0
	s_nop 0
	s_nop 0
	s_nop 0
	s_nop 0
	s_nop 0
	s_nop 0
	s_nop 0
	s_nop 0
	s_nop 0
	s_nop 0
	s_nop 0
	s_nop 0
	s_nop 0
	s_nop 0
	s_nop 0
	s_nop 0
	s_nop 0
	s_nop 0
	s_nop 0
	s_nop 0
	s_nop 0
	s_nop 0
	s_nop 0
	s_nop 0
